# hand-scheduled SwiGLU epilogue in both FFN-up phases: packed scale / +1 (v_pk_mul_f32, v_pk_add_f32), same per-element operations and rounding order
# speedup vs baseline: 1.0065x; 1.0065x over previous
.LBB0_173:
	s_mov_b32 s100, 0xbfb8aa3b
	v_lshl_or_b32 v166, s77, 7, v143
	v_lshl_add_u32 v168, s62, 8, v1
	v_ashrrev_i32_e32 v167, 31, v166
	v_mov_b64_e32 v[170:171], s[40:41]
	v_mad_i64_i32 v[170:171], s[64:65], v168, s76, v[170:171]
	v_lshlrev_b64 v[166:167], 1, v[166:167]
	s_lshl_b32 s98, s76, 4
	s_mov_b32 s99, 0
	v_lshl_add_u64 v[170:171], v[170:171], 0, v[166:167]
	s_lshl_b32 s96, s76, 7
	s_mov_b32 s97, 0
	v_lshl_add_u64 v[172:173], v[170:171], 0, s[96:97]
	v_pk_mul_f32 v[148:149], v[126:127], s[100:101] op_sel_hi:[1,0]
	v_pk_mul_f32 v[150:151], v[128:129], s[100:101] op_sel_hi:[1,0]
	v_pk_mul_f32 v[152:153], v[118:119], s[100:101] op_sel_hi:[1,0]
	v_pk_mul_f32 v[154:155], v[120:121], s[100:101] op_sel_hi:[1,0]
	v_exp_f32_e32 v148, v148
	v_exp_f32_e32 v149, v149
	v_exp_f32_e32 v150, v150
	v_exp_f32_e32 v151, v151
	v_exp_f32_e32 v152, v152
	v_exp_f32_e32 v153, v153
	v_exp_f32_e32 v154, v154
	v_exp_f32_e32 v155, v155
	v_pk_mul_f32 v[126:127], v[126:127], v[122:123]
	v_pk_mul_f32 v[128:129], v[128:129], v[124:125]
	v_pk_mul_f32 v[118:119], v[118:119], v[114:115]
	v_pk_mul_f32 v[120:121], v[120:121], v[116:117]
	v_pk_add_f32 v[148:149], v[148:149], 1.0 op_sel_hi:[1,0]
	v_pk_add_f32 v[150:151], v[150:151], 1.0 op_sel_hi:[1,0]
	v_pk_add_f32 v[152:153], v[152:153], 1.0 op_sel_hi:[1,0]
	v_pk_add_f32 v[154:155], v[154:155], 1.0 op_sel_hi:[1,0]
	v_rcp_f32_e32 v148, v148
	v_rcp_f32_e32 v149, v149
	v_rcp_f32_e32 v150, v150
	v_rcp_f32_e32 v151, v151
	v_rcp_f32_e32 v152, v152
	v_rcp_f32_e32 v153, v153
	v_rcp_f32_e32 v154, v154
	v_rcp_f32_e32 v155, v155
	s_nop 0
	v_pk_mul_f32 v[126:127], v[148:149], v[126:127]
	v_pk_mul_f32 v[128:129], v[150:151], v[128:129]
	v_pk_mul_f32 v[118:119], v[152:153], v[118:119]
	v_pk_mul_f32 v[120:121], v[154:155], v[120:121]
	v_cvt_pk_bf16_f32 v122, v126, v127
	v_cvt_pk_bf16_f32 v123, v128, v129
	v_cvt_pk_bf16_f32 v124, v118, v119
	v_cvt_pk_bf16_f32 v125, v120, v121
	global_store_dwordx4 v[170:171], v[122:125], off sc1
	v_lshl_add_u64 v[170:171], v[170:171], 0, s[98:99]
	v_pk_mul_f32 v[156:157], v[110:111], s[100:101] op_sel_hi:[1,0]
	v_pk_mul_f32 v[158:159], v[112:113], s[100:101] op_sel_hi:[1,0]
	v_pk_mul_f32 v[160:161], v[102:103], s[100:101] op_sel_hi:[1,0]
	v_pk_mul_f32 v[162:163], v[104:105], s[100:101] op_sel_hi:[1,0]
	v_exp_f32_e32 v156, v156
	v_exp_f32_e32 v157, v157
	v_exp_f32_e32 v158, v158
	v_exp_f32_e32 v159, v159
	v_exp_f32_e32 v160, v160
	v_exp_f32_e32 v161, v161
	v_exp_f32_e32 v162, v162
	v_exp_f32_e32 v163, v163
	v_pk_mul_f32 v[110:111], v[110:111], v[106:107]
	v_pk_mul_f32 v[112:113], v[112:113], v[108:109]
	v_pk_mul_f32 v[102:103], v[102:103], v[98:99]
	v_pk_mul_f32 v[104:105], v[104:105], v[100:101]
	v_pk_add_f32 v[156:157], v[156:157], 1.0 op_sel_hi:[1,0]
	v_pk_add_f32 v[158:159], v[158:159], 1.0 op_sel_hi:[1,0]
	v_pk_add_f32 v[160:161], v[160:161], 1.0 op_sel_hi:[1,0]
	v_pk_add_f32 v[162:163], v[162:163], 1.0 op_sel_hi:[1,0]
	v_rcp_f32_e32 v156, v156
	v_rcp_f32_e32 v157, v157
	v_rcp_f32_e32 v158, v158
	v_rcp_f32_e32 v159, v159
	v_rcp_f32_e32 v160, v160
	v_rcp_f32_e32 v161, v161
	v_rcp_f32_e32 v162, v162
	v_rcp_f32_e32 v163, v163
	s_nop 0
	v_pk_mul_f32 v[110:111], v[156:157], v[110:111]
	v_pk_mul_f32 v[112:113], v[158:159], v[112:113]
	v_pk_mul_f32 v[102:103], v[160:161], v[102:103]
	v_pk_mul_f32 v[104:105], v[162:163], v[104:105]
	v_cvt_pk_bf16_f32 v106, v110, v111
	v_cvt_pk_bf16_f32 v107, v112, v113
	v_cvt_pk_bf16_f32 v108, v102, v103
	v_cvt_pk_bf16_f32 v109, v104, v105
	global_store_dwordx4 v[170:171], v[106:109], off sc1
	v_lshl_add_u64 v[170:171], v[170:171], 0, s[98:99]
	v_pk_mul_f32 v[148:149], v[94:95], s[100:101] op_sel_hi:[1,0]
	v_pk_mul_f32 v[150:151], v[96:97], s[100:101] op_sel_hi:[1,0]
	v_pk_mul_f32 v[152:153], v[86:87], s[100:101] op_sel_hi:[1,0]
	v_pk_mul_f32 v[154:155], v[88:89], s[100:101] op_sel_hi:[1,0]
	v_exp_f32_e32 v148, v148
	v_exp_f32_e32 v149, v149
	v_exp_f32_e32 v150, v150
	v_exp_f32_e32 v151, v151
	v_exp_f32_e32 v152, v152
	v_exp_f32_e32 v153, v153
	v_exp_f32_e32 v154, v154
	v_exp_f32_e32 v155, v155
	v_pk_mul_f32 v[94:95], v[94:95], v[90:91]
	v_pk_mul_f32 v[96:97], v[96:97], v[92:93]
	v_pk_mul_f32 v[86:87], v[86:87], v[82:83]
	v_pk_mul_f32 v[88:89], v[88:89], v[84:85]
	v_pk_add_f32 v[148:149], v[148:149], 1.0 op_sel_hi:[1,0]
	v_pk_add_f32 v[150:151], v[150:151], 1.0 op_sel_hi:[1,0]
	v_pk_add_f32 v[152:153], v[152:153], 1.0 op_sel_hi:[1,0]
	v_pk_add_f32 v[154:155], v[154:155], 1.0 op_sel_hi:[1,0]
	v_rcp_f32_e32 v148, v148
	v_rcp_f32_e32 v149, v149
	v_rcp_f32_e32 v150, v150
	v_rcp_f32_e32 v151, v151
	v_rcp_f32_e32 v152, v152
	v_rcp_f32_e32 v153, v153
	v_rcp_f32_e32 v154, v154
	v_rcp_f32_e32 v155, v155
	s_nop 0
	v_pk_mul_f32 v[94:95], v[148:149], v[94:95]
	v_pk_mul_f32 v[96:97], v[150:151], v[96:97]
	v_pk_mul_f32 v[86:87], v[152:153], v[86:87]
	v_pk_mul_f32 v[88:89], v[154:155], v[88:89]
	v_cvt_pk_bf16_f32 v90, v94, v95
	v_cvt_pk_bf16_f32 v91, v96, v97
	v_cvt_pk_bf16_f32 v92, v86, v87
	v_cvt_pk_bf16_f32 v93, v88, v89
	global_store_dwordx4 v[170:171], v[90:93], off sc1
	v_lshl_add_u64 v[170:171], v[170:171], 0, s[98:99]
	v_pk_mul_f32 v[156:157], v[78:79], s[100:101] op_sel_hi:[1,0]
	v_pk_mul_f32 v[158:159], v[80:81], s[100:101] op_sel_hi:[1,0]
	v_pk_mul_f32 v[160:161], v[70:71], s[100:101] op_sel_hi:[1,0]
	v_pk_mul_f32 v[162:163], v[72:73], s[100:101] op_sel_hi:[1,0]
	v_exp_f32_e32 v156, v156
	v_exp_f32_e32 v157, v157
	v_exp_f32_e32 v158, v158
	v_exp_f32_e32 v159, v159
	v_exp_f32_e32 v160, v160
	v_exp_f32_e32 v161, v161
	v_exp_f32_e32 v162, v162
	v_exp_f32_e32 v163, v163
	v_pk_mul_f32 v[78:79], v[78:79], v[74:75]
	v_pk_mul_f32 v[80:81], v[80:81], v[76:77]
	v_pk_mul_f32 v[70:71], v[70:71], v[66:67]
	v_pk_mul_f32 v[72:73], v[72:73], v[68:69]
	v_pk_add_f32 v[156:157], v[156:157], 1.0 op_sel_hi:[1,0]
	v_pk_add_f32 v[158:159], v[158:159], 1.0 op_sel_hi:[1,0]
	v_pk_add_f32 v[160:161], v[160:161], 1.0 op_sel_hi:[1,0]
	v_pk_add_f32 v[162:163], v[162:163], 1.0 op_sel_hi:[1,0]
	v_rcp_f32_e32 v156, v156
	v_rcp_f32_e32 v157, v157
	v_rcp_f32_e32 v158, v158
	v_rcp_f32_e32 v159, v159
	v_rcp_f32_e32 v160, v160
	v_rcp_f32_e32 v161, v161
	v_rcp_f32_e32 v162, v162
	v_rcp_f32_e32 v163, v163
	s_nop 0
	v_pk_mul_f32 v[78:79], v[156:157], v[78:79]
	v_pk_mul_f32 v[80:81], v[158:159], v[80:81]
	v_pk_mul_f32 v[70:71], v[160:161], v[70:71]
	v_pk_mul_f32 v[72:73], v[162:163], v[72:73]
	v_cvt_pk_bf16_f32 v74, v78, v79
	v_cvt_pk_bf16_f32 v75, v80, v81
	v_cvt_pk_bf16_f32 v76, v70, v71
	v_cvt_pk_bf16_f32 v77, v72, v73
	global_store_dwordx4 v[170:171], v[74:77], off sc1
	v_pk_mul_f32 v[148:149], v[62:63], s[100:101] op_sel_hi:[1,0]
	v_pk_mul_f32 v[150:151], v[64:65], s[100:101] op_sel_hi:[1,0]
	v_pk_mul_f32 v[152:153], v[54:55], s[100:101] op_sel_hi:[1,0]
	v_pk_mul_f32 v[154:155], v[56:57], s[100:101] op_sel_hi:[1,0]
	v_exp_f32_e32 v148, v148
	v_exp_f32_e32 v149, v149
	v_exp_f32_e32 v150, v150
	v_exp_f32_e32 v151, v151
	v_exp_f32_e32 v152, v152
	v_exp_f32_e32 v153, v153
	v_exp_f32_e32 v154, v154
	v_exp_f32_e32 v155, v155
	v_pk_mul_f32 v[62:63], v[62:63], v[58:59]
	v_pk_mul_f32 v[64:65], v[64:65], v[60:61]
	v_pk_mul_f32 v[54:55], v[54:55], v[50:51]
	v_pk_mul_f32 v[56:57], v[56:57], v[52:53]
	v_pk_add_f32 v[148:149], v[148:149], 1.0 op_sel_hi:[1,0]
	v_pk_add_f32 v[150:151], v[150:151], 1.0 op_sel_hi:[1,0]
	v_pk_add_f32 v[152:153], v[152:153], 1.0 op_sel_hi:[1,0]
	v_pk_add_f32 v[154:155], v[154:155], 1.0 op_sel_hi:[1,0]
	v_rcp_f32_e32 v148, v148
	v_rcp_f32_e32 v149, v149
	v_rcp_f32_e32 v150, v150
	v_rcp_f32_e32 v151, v151
	v_rcp_f32_e32 v152, v152
	v_rcp_f32_e32 v153, v153
	v_rcp_f32_e32 v154, v154
	v_rcp_f32_e32 v155, v155
	s_nop 0
	v_pk_mul_f32 v[62:63], v[148:149], v[62:63]
	v_pk_mul_f32 v[64:65], v[150:151], v[64:65]
	v_pk_mul_f32 v[54:55], v[152:153], v[54:55]
	v_pk_mul_f32 v[56:57], v[154:155], v[56:57]
	v_cvt_pk_bf16_f32 v58, v62, v63
	v_cvt_pk_bf16_f32 v59, v64, v65
	v_cvt_pk_bf16_f32 v60, v54, v55
	v_cvt_pk_bf16_f32 v61, v56, v57
	global_store_dwordx4 v[172:173], v[58:61], off sc1
	v_lshl_add_u64 v[172:173], v[172:173], 0, s[98:99]
	v_pk_mul_f32 v[156:157], v[46:47], s[100:101] op_sel_hi:[1,0]
	v_pk_mul_f32 v[158:159], v[48:49], s[100:101] op_sel_hi:[1,0]
	v_pk_mul_f32 v[160:161], v[38:39], s[100:101] op_sel_hi:[1,0]
	v_pk_mul_f32 v[162:163], v[40:41], s[100:101] op_sel_hi:[1,0]
	v_exp_f32_e32 v156, v156
	v_exp_f32_e32 v157, v157
	v_exp_f32_e32 v158, v158
	v_exp_f32_e32 v159, v159
	v_exp_f32_e32 v160, v160
	v_exp_f32_e32 v161, v161
	v_exp_f32_e32 v162, v162
	v_exp_f32_e32 v163, v163
	v_pk_mul_f32 v[46:47], v[46:47], v[42:43]
	v_pk_mul_f32 v[48:49], v[48:49], v[44:45]
	v_pk_mul_f32 v[38:39], v[38:39], v[34:35]
	v_pk_mul_f32 v[40:41], v[40:41], v[36:37]
	v_pk_add_f32 v[156:157], v[156:157], 1.0 op_sel_hi:[1,0]
	v_pk_add_f32 v[158:159], v[158:159], 1.0 op_sel_hi:[1,0]
	v_pk_add_f32 v[160:161], v[160:161], 1.0 op_sel_hi:[1,0]
	v_pk_add_f32 v[162:163], v[162:163], 1.0 op_sel_hi:[1,0]
	v_rcp_f32_e32 v156, v156
	v_rcp_f32_e32 v157, v157
	v_rcp_f32_e32 v158, v158
	v_rcp_f32_e32 v159, v159
	v_rcp_f32_e32 v160, v160
	v_rcp_f32_e32 v161, v161
	v_rcp_f32_e32 v162, v162
	v_rcp_f32_e32 v163, v163
	s_nop 0
	v_pk_mul_f32 v[46:47], v[156:157], v[46:47]
	v_pk_mul_f32 v[48:49], v[158:159], v[48:49]
	v_pk_mul_f32 v[38:39], v[160:161], v[38:39]
	v_pk_mul_f32 v[40:41], v[162:163], v[40:41]
	v_cvt_pk_bf16_f32 v42, v46, v47
	v_cvt_pk_bf16_f32 v43, v48, v49
	v_cvt_pk_bf16_f32 v44, v38, v39
	v_cvt_pk_bf16_f32 v45, v40, v41
	global_store_dwordx4 v[172:173], v[42:45], off sc1
	v_lshl_add_u64 v[172:173], v[172:173], 0, s[98:99]
	v_pk_mul_f32 v[148:149], v[30:31], s[100:101] op_sel_hi:[1,0]
	v_pk_mul_f32 v[150:151], v[32:33], s[100:101] op_sel_hi:[1,0]
	v_pk_mul_f32 v[152:153], v[22:23], s[100:101] op_sel_hi:[1,0]
	v_pk_mul_f32 v[154:155], v[24:25], s[100:101] op_sel_hi:[1,0]
	v_exp_f32_e32 v148, v148
	v_exp_f32_e32 v149, v149
	v_exp_f32_e32 v150, v150
	v_exp_f32_e32 v151, v151
	v_exp_f32_e32 v152, v152
	v_exp_f32_e32 v153, v153
	v_exp_f32_e32 v154, v154
	v_exp_f32_e32 v155, v155
	v_pk_mul_f32 v[30:31], v[30:31], v[26:27]
	v_pk_mul_f32 v[32:33], v[32:33], v[28:29]
	v_pk_mul_f32 v[22:23], v[22:23], v[18:19]
	v_pk_mul_f32 v[24:25], v[24:25], v[20:21]
	v_pk_add_f32 v[148:149], v[148:149], 1.0 op_sel_hi:[1,0]
	v_pk_add_f32 v[150:151], v[150:151], 1.0 op_sel_hi:[1,0]
	v_pk_add_f32 v[152:153], v[152:153], 1.0 op_sel_hi:[1,0]
	v_pk_add_f32 v[154:155], v[154:155], 1.0 op_sel_hi:[1,0]
	v_rcp_f32_e32 v148, v148
	v_rcp_f32_e32 v149, v149
	v_rcp_f32_e32 v150, v150
	v_rcp_f32_e32 v151, v151
	v_rcp_f32_e32 v152, v152
	v_rcp_f32_e32 v153, v153
	v_rcp_f32_e32 v154, v154
	v_rcp_f32_e32 v155, v155
	s_nop 0
	v_pk_mul_f32 v[30:31], v[148:149], v[30:31]
	v_pk_mul_f32 v[32:33], v[150:151], v[32:33]
	v_pk_mul_f32 v[22:23], v[152:153], v[22:23]
	v_pk_mul_f32 v[24:25], v[154:155], v[24:25]
	v_cvt_pk_bf16_f32 v26, v30, v31
	v_cvt_pk_bf16_f32 v27, v32, v33
	v_cvt_pk_bf16_f32 v28, v22, v23
	v_cvt_pk_bf16_f32 v29, v24, v25
	global_store_dwordx4 v[172:173], v[26:29], off sc1
	v_lshl_add_u64 v[172:173], v[172:173], 0, s[98:99]
	v_pk_mul_f32 v[156:157], v[14:15], s[100:101] op_sel_hi:[1,0]
	v_pk_mul_f32 v[158:159], v[16:17], s[100:101] op_sel_hi:[1,0]
	v_pk_mul_f32 v[160:161], v[6:7], s[100:101] op_sel_hi:[1,0]
	v_pk_mul_f32 v[162:163], v[8:9], s[100:101] op_sel_hi:[1,0]
	v_exp_f32_e32 v156, v156
	v_exp_f32_e32 v157, v157
	v_exp_f32_e32 v158, v158
	v_exp_f32_e32 v159, v159
	v_exp_f32_e32 v160, v160
	v_exp_f32_e32 v161, v161
	v_exp_f32_e32 v162, v162
	v_exp_f32_e32 v163, v163
	v_pk_mul_f32 v[14:15], v[14:15], v[10:11]
	v_pk_mul_f32 v[16:17], v[16:17], v[12:13]
	v_pk_mul_f32 v[6:7], v[6:7], v[2:3]
	v_pk_mul_f32 v[8:9], v[8:9], v[4:5]
	v_pk_add_f32 v[156:157], v[156:157], 1.0 op_sel_hi:[1,0]
	v_pk_add_f32 v[158:159], v[158:159], 1.0 op_sel_hi:[1,0]
	v_pk_add_f32 v[160:161], v[160:161], 1.0 op_sel_hi:[1,0]
	v_pk_add_f32 v[162:163], v[162:163], 1.0 op_sel_hi:[1,0]
	v_rcp_f32_e32 v156, v156
	v_rcp_f32_e32 v157, v157
	v_rcp_f32_e32 v158, v158
	v_rcp_f32_e32 v159, v159
	v_rcp_f32_e32 v160, v160
	v_rcp_f32_e32 v161, v161
	v_rcp_f32_e32 v162, v162
	v_rcp_f32_e32 v163, v163
	s_nop 0
	v_pk_mul_f32 v[14:15], v[156:157], v[14:15]
	v_pk_mul_f32 v[16:17], v[158:159], v[16:17]
	v_pk_mul_f32 v[6:7], v[160:161], v[6:7]
	v_pk_mul_f32 v[8:9], v[162:163], v[8:9]
	v_cvt_pk_bf16_f32 v10, v14, v15
	v_cvt_pk_bf16_f32 v11, v16, v17
	v_cvt_pk_bf16_f32 v12, v6, v7
	v_cvt_pk_bf16_f32 v13, v8, v9
	global_store_dwordx4 v[172:173], v[10:13], off sc1
	s_andn2_b64 vcc, exec, s[0:1]
	s_mov_b64 s[0:1], -1
	s_cbranch_vccnz .LBB0_166
	s_andn2_b64 vcc, exec, s[6:7]
	s_cbranch_vccnz .LBB0_165
	s_barrier
	s_branch .LBB0_165

.LBB0_980:
	s_mov_b32 s100, 0xbfb8aa3b
	v_lshl_or_b32 v166, s59, 7, v143
	v_lshl_add_u32 v168, s22, 8, v1
	v_ashrrev_i32_e32 v167, 31, v166
	v_mov_b64_e32 v[170:171], s[40:41]
	v_mad_i64_i32 v[170:171], s[24:25], v168, s58, v[170:171]
	v_lshlrev_b64 v[166:167], 1, v[166:167]
	s_lshl_b32 s98, s58, 4
	s_mov_b32 s99, 0
	v_lshl_add_u64 v[170:171], v[170:171], 0, v[166:167]
	s_lshl_b32 s96, s58, 7
	s_mov_b32 s97, 0
	v_lshl_add_u64 v[172:173], v[170:171], 0, s[96:97]
	v_pk_mul_f32 v[148:149], v[126:127], s[100:101] op_sel_hi:[1,0]
	v_pk_mul_f32 v[150:151], v[128:129], s[100:101] op_sel_hi:[1,0]
	v_pk_mul_f32 v[152:153], v[118:119], s[100:101] op_sel_hi:[1,0]
	v_pk_mul_f32 v[154:155], v[120:121], s[100:101] op_sel_hi:[1,0]
	v_exp_f32_e32 v148, v148
	v_exp_f32_e32 v149, v149
	v_exp_f32_e32 v150, v150
	v_exp_f32_e32 v151, v151
	v_exp_f32_e32 v152, v152
	v_exp_f32_e32 v153, v153
	v_exp_f32_e32 v154, v154
	v_exp_f32_e32 v155, v155
	v_pk_mul_f32 v[126:127], v[126:127], v[122:123]
	v_pk_mul_f32 v[128:129], v[128:129], v[124:125]
	v_pk_mul_f32 v[118:119], v[118:119], v[114:115]
	v_pk_mul_f32 v[120:121], v[120:121], v[116:117]
	v_pk_add_f32 v[148:149], v[148:149], 1.0 op_sel_hi:[1,0]
	v_pk_add_f32 v[150:151], v[150:151], 1.0 op_sel_hi:[1,0]
	v_pk_add_f32 v[152:153], v[152:153], 1.0 op_sel_hi:[1,0]
	v_pk_add_f32 v[154:155], v[154:155], 1.0 op_sel_hi:[1,0]
	v_rcp_f32_e32 v148, v148
	v_rcp_f32_e32 v149, v149
	v_rcp_f32_e32 v150, v150
	v_rcp_f32_e32 v151, v151
	v_rcp_f32_e32 v152, v152
	v_rcp_f32_e32 v153, v153
	v_rcp_f32_e32 v154, v154
	v_rcp_f32_e32 v155, v155
	s_nop 0
	v_pk_mul_f32 v[126:127], v[148:149], v[126:127]
	v_pk_mul_f32 v[128:129], v[150:151], v[128:129]
	v_pk_mul_f32 v[118:119], v[152:153], v[118:119]
	v_pk_mul_f32 v[120:121], v[154:155], v[120:121]
	v_cvt_pk_bf16_f32 v122, v126, v127
	v_cvt_pk_bf16_f32 v123, v128, v129
	v_cvt_pk_bf16_f32 v124, v118, v119
	v_cvt_pk_bf16_f32 v125, v120, v121
	global_store_dwordx4 v[170:171], v[122:125], off sc1
	v_lshl_add_u64 v[170:171], v[170:171], 0, s[98:99]
	v_pk_mul_f32 v[156:157], v[110:111], s[100:101] op_sel_hi:[1,0]
	v_pk_mul_f32 v[158:159], v[112:113], s[100:101] op_sel_hi:[1,0]
	v_pk_mul_f32 v[160:161], v[102:103], s[100:101] op_sel_hi:[1,0]
	v_pk_mul_f32 v[162:163], v[104:105], s[100:101] op_sel_hi:[1,0]
	v_exp_f32_e32 v156, v156
	v_exp_f32_e32 v157, v157
	v_exp_f32_e32 v158, v158
	v_exp_f32_e32 v159, v159
	v_exp_f32_e32 v160, v160
	v_exp_f32_e32 v161, v161
	v_exp_f32_e32 v162, v162
	v_exp_f32_e32 v163, v163
	v_pk_mul_f32 v[110:111], v[110:111], v[106:107]
	v_pk_mul_f32 v[112:113], v[112:113], v[108:109]
	v_pk_mul_f32 v[102:103], v[102:103], v[98:99]
	v_pk_mul_f32 v[104:105], v[104:105], v[100:101]
	v_pk_add_f32 v[156:157], v[156:157], 1.0 op_sel_hi:[1,0]
	v_pk_add_f32 v[158:159], v[158:159], 1.0 op_sel_hi:[1,0]
	v_pk_add_f32 v[160:161], v[160:161], 1.0 op_sel_hi:[1,0]
	v_pk_add_f32 v[162:163], v[162:163], 1.0 op_sel_hi:[1,0]
	v_rcp_f32_e32 v156, v156
	v_rcp_f32_e32 v157, v157
	v_rcp_f32_e32 v158, v158
	v_rcp_f32_e32 v159, v159
	v_rcp_f32_e32 v160, v160
	v_rcp_f32_e32 v161, v161
	v_rcp_f32_e32 v162, v162
	v_rcp_f32_e32 v163, v163
	s_nop 0
	v_pk_mul_f32 v[110:111], v[156:157], v[110:111]
	v_pk_mul_f32 v[112:113], v[158:159], v[112:113]
	v_pk_mul_f32 v[102:103], v[160:161], v[102:103]
	v_pk_mul_f32 v[104:105], v[162:163], v[104:105]
	v_cvt_pk_bf16_f32 v106, v110, v111
	v_cvt_pk_bf16_f32 v107, v112, v113
	v_cvt_pk_bf16_f32 v108, v102, v103
	v_cvt_pk_bf16_f32 v109, v104, v105
	global_store_dwordx4 v[170:171], v[106:109], off sc1
	v_lshl_add_u64 v[170:171], v[170:171], 0, s[98:99]
	v_pk_mul_f32 v[148:149], v[94:95], s[100:101] op_sel_hi:[1,0]
	v_pk_mul_f32 v[150:151], v[96:97], s[100:101] op_sel_hi:[1,0]
	v_pk_mul_f32 v[152:153], v[86:87], s[100:101] op_sel_hi:[1,0]
	v_pk_mul_f32 v[154:155], v[88:89], s[100:101] op_sel_hi:[1,0]
	v_exp_f32_e32 v148, v148
	v_exp_f32_e32 v149, v149
	v_exp_f32_e32 v150, v150
	v_exp_f32_e32 v151, v151
	v_exp_f32_e32 v152, v152
	v_exp_f32_e32 v153, v153
	v_exp_f32_e32 v154, v154
	v_exp_f32_e32 v155, v155
	v_pk_mul_f32 v[94:95], v[94:95], v[90:91]
	v_pk_mul_f32 v[96:97], v[96:97], v[92:93]
	v_pk_mul_f32 v[86:87], v[86:87], v[82:83]
	v_pk_mul_f32 v[88:89], v[88:89], v[84:85]
	v_pk_add_f32 v[148:149], v[148:149], 1.0 op_sel_hi:[1,0]
	v_pk_add_f32 v[150:151], v[150:151], 1.0 op_sel_hi:[1,0]
	v_pk_add_f32 v[152:153], v[152:153], 1.0 op_sel_hi:[1,0]
	v_pk_add_f32 v[154:155], v[154:155], 1.0 op_sel_hi:[1,0]
	v_rcp_f32_e32 v148, v148
	v_rcp_f32_e32 v149, v149
	v_rcp_f32_e32 v150, v150
	v_rcp_f32_e32 v151, v151
	v_rcp_f32_e32 v152, v152
	v_rcp_f32_e32 v153, v153
	v_rcp_f32_e32 v154, v154
	v_rcp_f32_e32 v155, v155
	s_nop 0
	v_pk_mul_f32 v[94:95], v[148:149], v[94:95]
	v_pk_mul_f32 v[96:97], v[150:151], v[96:97]
	v_pk_mul_f32 v[86:87], v[152:153], v[86:87]
	v_pk_mul_f32 v[88:89], v[154:155], v[88:89]
	v_cvt_pk_bf16_f32 v90, v94, v95
	v_cvt_pk_bf16_f32 v91, v96, v97
	v_cvt_pk_bf16_f32 v92, v86, v87
	v_cvt_pk_bf16_f32 v93, v88, v89
	global_store_dwordx4 v[170:171], v[90:93], off sc1
	v_lshl_add_u64 v[170:171], v[170:171], 0, s[98:99]
	v_pk_mul_f32 v[156:157], v[78:79], s[100:101] op_sel_hi:[1,0]
	v_pk_mul_f32 v[158:159], v[80:81], s[100:101] op_sel_hi:[1,0]
	v_pk_mul_f32 v[160:161], v[70:71], s[100:101] op_sel_hi:[1,0]
	v_pk_mul_f32 v[162:163], v[72:73], s[100:101] op_sel_hi:[1,0]
	v_exp_f32_e32 v156, v156
	v_exp_f32_e32 v157, v157
	v_exp_f32_e32 v158, v158
	v_exp_f32_e32 v159, v159
	v_exp_f32_e32 v160, v160
	v_exp_f32_e32 v161, v161
	v_exp_f32_e32 v162, v162
	v_exp_f32_e32 v163, v163
	v_pk_mul_f32 v[78:79], v[78:79], v[74:75]
	v_pk_mul_f32 v[80:81], v[80:81], v[76:77]
	v_pk_mul_f32 v[70:71], v[70:71], v[66:67]
	v_pk_mul_f32 v[72:73], v[72:73], v[68:69]
	v_pk_add_f32 v[156:157], v[156:157], 1.0 op_sel_hi:[1,0]
	v_pk_add_f32 v[158:159], v[158:159], 1.0 op_sel_hi:[1,0]
	v_pk_add_f32 v[160:161], v[160:161], 1.0 op_sel_hi:[1,0]
	v_pk_add_f32 v[162:163], v[162:163], 1.0 op_sel_hi:[1,0]
	v_rcp_f32_e32 v156, v156
	v_rcp_f32_e32 v157, v157
	v_rcp_f32_e32 v158, v158
	v_rcp_f32_e32 v159, v159
	v_rcp_f32_e32 v160, v160
	v_rcp_f32_e32 v161, v161
	v_rcp_f32_e32 v162, v162
	v_rcp_f32_e32 v163, v163
	s_nop 0
	v_pk_mul_f32 v[78:79], v[156:157], v[78:79]
	v_pk_mul_f32 v[80:81], v[158:159], v[80:81]
	v_pk_mul_f32 v[70:71], v[160:161], v[70:71]
	v_pk_mul_f32 v[72:73], v[162:163], v[72:73]
	v_cvt_pk_bf16_f32 v74, v78, v79
	v_cvt_pk_bf16_f32 v75, v80, v81
	v_cvt_pk_bf16_f32 v76, v70, v71
	v_cvt_pk_bf16_f32 v77, v72, v73
	global_store_dwordx4 v[170:171], v[74:77], off sc1
	v_pk_mul_f32 v[148:149], v[62:63], s[100:101] op_sel_hi:[1,0]
	v_pk_mul_f32 v[150:151], v[64:65], s[100:101] op_sel_hi:[1,0]
	v_pk_mul_f32 v[152:153], v[54:55], s[100:101] op_sel_hi:[1,0]
	v_pk_mul_f32 v[154:155], v[56:57], s[100:101] op_sel_hi:[1,0]
	v_exp_f32_e32 v148, v148
	v_exp_f32_e32 v149, v149
	v_exp_f32_e32 v150, v150
	v_exp_f32_e32 v151, v151
	v_exp_f32_e32 v152, v152
	v_exp_f32_e32 v153, v153
	v_exp_f32_e32 v154, v154
	v_exp_f32_e32 v155, v155
	v_pk_mul_f32 v[62:63], v[62:63], v[58:59]
	v_pk_mul_f32 v[64:65], v[64:65], v[60:61]
	v_pk_mul_f32 v[54:55], v[54:55], v[50:51]
	v_pk_mul_f32 v[56:57], v[56:57], v[52:53]
	v_pk_add_f32 v[148:149], v[148:149], 1.0 op_sel_hi:[1,0]
	v_pk_add_f32 v[150:151], v[150:151], 1.0 op_sel_hi:[1,0]
	v_pk_add_f32 v[152:153], v[152:153], 1.0 op_sel_hi:[1,0]
	v_pk_add_f32 v[154:155], v[154:155], 1.0 op_sel_hi:[1,0]
	v_rcp_f32_e32 v148, v148
	v_rcp_f32_e32 v149, v149
	v_rcp_f32_e32 v150, v150
	v_rcp_f32_e32 v151, v151
	v_rcp_f32_e32 v152, v152
	v_rcp_f32_e32 v153, v153
	v_rcp_f32_e32 v154, v154
	v_rcp_f32_e32 v155, v155
	s_nop 0
	v_pk_mul_f32 v[62:63], v[148:149], v[62:63]
	v_pk_mul_f32 v[64:65], v[150:151], v[64:65]
	v_pk_mul_f32 v[54:55], v[152:153], v[54:55]
	v_pk_mul_f32 v[56:57], v[154:155], v[56:57]
	v_cvt_pk_bf16_f32 v58, v62, v63
	v_cvt_pk_bf16_f32 v59, v64, v65
	v_cvt_pk_bf16_f32 v60, v54, v55
	v_cvt_pk_bf16_f32 v61, v56, v57
	global_store_dwordx4 v[172:173], v[58:61], off sc1
	v_lshl_add_u64 v[172:173], v[172:173], 0, s[98:99]
	v_pk_mul_f32 v[156:157], v[46:47], s[100:101] op_sel_hi:[1,0]
	v_pk_mul_f32 v[158:159], v[48:49], s[100:101] op_sel_hi:[1,0]
	v_pk_mul_f32 v[160:161], v[38:39], s[100:101] op_sel_hi:[1,0]
	v_pk_mul_f32 v[162:163], v[40:41], s[100:101] op_sel_hi:[1,0]
	v_exp_f32_e32 v156, v156
	v_exp_f32_e32 v157, v157
	v_exp_f32_e32 v158, v158
	v_exp_f32_e32 v159, v159
	v_exp_f32_e32 v160, v160
	v_exp_f32_e32 v161, v161
	v_exp_f32_e32 v162, v162
	v_exp_f32_e32 v163, v163
	v_pk_mul_f32 v[46:47], v[46:47], v[42:43]
	v_pk_mul_f32 v[48:49], v[48:49], v[44:45]
	v_pk_mul_f32 v[38:39], v[38:39], v[34:35]
	v_pk_mul_f32 v[40:41], v[40:41], v[36:37]
	v_pk_add_f32 v[156:157], v[156:157], 1.0 op_sel_hi:[1,0]
	v_pk_add_f32 v[158:159], v[158:159], 1.0 op_sel_hi:[1,0]
	v_pk_add_f32 v[160:161], v[160:161], 1.0 op_sel_hi:[1,0]
	v_pk_add_f32 v[162:163], v[162:163], 1.0 op_sel_hi:[1,0]
	v_rcp_f32_e32 v156, v156
	v_rcp_f32_e32 v157, v157
	v_rcp_f32_e32 v158, v158
	v_rcp_f32_e32 v159, v159
	v_rcp_f32_e32 v160, v160
	v_rcp_f32_e32 v161, v161
	v_rcp_f32_e32 v162, v162
	v_rcp_f32_e32 v163, v163
	s_nop 0
	v_pk_mul_f32 v[46:47], v[156:157], v[46:47]
	v_pk_mul_f32 v[48:49], v[158:159], v[48:49]
	v_pk_mul_f32 v[38:39], v[160:161], v[38:39]
	v_pk_mul_f32 v[40:41], v[162:163], v[40:41]
	v_cvt_pk_bf16_f32 v42, v46, v47
	v_cvt_pk_bf16_f32 v43, v48, v49
	v_cvt_pk_bf16_f32 v44, v38, v39
	v_cvt_pk_bf16_f32 v45, v40, v41
	global_store_dwordx4 v[172:173], v[42:45], off sc1
	v_lshl_add_u64 v[172:173], v[172:173], 0, s[98:99]
	v_pk_mul_f32 v[148:149], v[30:31], s[100:101] op_sel_hi:[1,0]
	v_pk_mul_f32 v[150:151], v[32:33], s[100:101] op_sel_hi:[1,0]
	v_pk_mul_f32 v[152:153], v[22:23], s[100:101] op_sel_hi:[1,0]
	v_pk_mul_f32 v[154:155], v[24:25], s[100:101] op_sel_hi:[1,0]
	v_exp_f32_e32 v148, v148
	v_exp_f32_e32 v149, v149
	v_exp_f32_e32 v150, v150
	v_exp_f32_e32 v151, v151
	v_exp_f32_e32 v152, v152
	v_exp_f32_e32 v153, v153
	v_exp_f32_e32 v154, v154
	v_exp_f32_e32 v155, v155
	v_pk_mul_f32 v[30:31], v[30:31], v[26:27]
	v_pk_mul_f32 v[32:33], v[32:33], v[28:29]
	v_pk_mul_f32 v[22:23], v[22:23], v[18:19]
	v_pk_mul_f32 v[24:25], v[24:25], v[20:21]
	v_pk_add_f32 v[148:149], v[148:149], 1.0 op_sel_hi:[1,0]
	v_pk_add_f32 v[150:151], v[150:151], 1.0 op_sel_hi:[1,0]
	v_pk_add_f32 v[152:153], v[152:153], 1.0 op_sel_hi:[1,0]
	v_pk_add_f32 v[154:155], v[154:155], 1.0 op_sel_hi:[1,0]
	v_rcp_f32_e32 v148, v148
	v_rcp_f32_e32 v149, v149
	v_rcp_f32_e32 v150, v150
	v_rcp_f32_e32 v151, v151
	v_rcp_f32_e32 v152, v152
	v_rcp_f32_e32 v153, v153
	v_rcp_f32_e32 v154, v154
	v_rcp_f32_e32 v155, v155
	s_nop 0
	v_pk_mul_f32 v[30:31], v[148:149], v[30:31]
	v_pk_mul_f32 v[32:33], v[150:151], v[32:33]
	v_pk_mul_f32 v[22:23], v[152:153], v[22:23]
	v_pk_mul_f32 v[24:25], v[154:155], v[24:25]
	v_cvt_pk_bf16_f32 v26, v30, v31
	v_cvt_pk_bf16_f32 v27, v32, v33
	v_cvt_pk_bf16_f32 v28, v22, v23
	v_cvt_pk_bf16_f32 v29, v24, v25
	global_store_dwordx4 v[172:173], v[26:29], off sc1
	v_lshl_add_u64 v[172:173], v[172:173], 0, s[98:99]
	v_pk_mul_f32 v[156:157], v[14:15], s[100:101] op_sel_hi:[1,0]
	v_pk_mul_f32 v[158:159], v[16:17], s[100:101] op_sel_hi:[1,0]
	v_pk_mul_f32 v[160:161], v[6:7], s[100:101] op_sel_hi:[1,0]
	v_pk_mul_f32 v[162:163], v[8:9], s[100:101] op_sel_hi:[1,0]
	v_exp_f32_e32 v156, v156
	v_exp_f32_e32 v157, v157
	v_exp_f32_e32 v158, v158
	v_exp_f32_e32 v159, v159
	v_exp_f32_e32 v160, v160
	v_exp_f32_e32 v161, v161
	v_exp_f32_e32 v162, v162
	v_exp_f32_e32 v163, v163
	v_pk_mul_f32 v[14:15], v[14:15], v[10:11]
	v_pk_mul_f32 v[16:17], v[16:17], v[12:13]
	v_pk_mul_f32 v[6:7], v[6:7], v[2:3]
	v_pk_mul_f32 v[8:9], v[8:9], v[4:5]
	v_pk_add_f32 v[156:157], v[156:157], 1.0 op_sel_hi:[1,0]
	v_pk_add_f32 v[158:159], v[158:159], 1.0 op_sel_hi:[1,0]
	v_pk_add_f32 v[160:161], v[160:161], 1.0 op_sel_hi:[1,0]
	v_pk_add_f32 v[162:163], v[162:163], 1.0 op_sel_hi:[1,0]
	v_rcp_f32_e32 v156, v156
	v_rcp_f32_e32 v157, v157
	v_rcp_f32_e32 v158, v158
	v_rcp_f32_e32 v159, v159
	v_rcp_f32_e32 v160, v160
	v_rcp_f32_e32 v161, v161
	v_rcp_f32_e32 v162, v162
	v_rcp_f32_e32 v163, v163
	s_nop 0
	v_pk_mul_f32 v[14:15], v[156:157], v[14:15]
	v_pk_mul_f32 v[16:17], v[158:159], v[16:17]
	v_pk_mul_f32 v[6:7], v[160:161], v[6:7]
	v_pk_mul_f32 v[8:9], v[162:163], v[8:9]
	v_cvt_pk_bf16_f32 v10, v14, v15
	v_cvt_pk_bf16_f32 v11, v16, v17
	v_cvt_pk_bf16_f32 v12, v6, v7
	v_cvt_pk_bf16_f32 v13, v8, v9
	global_store_dwordx4 v[172:173], v[10:13], off sc1
	s_andn2_b64 vcc, exec, s[0:1]
	s_mov_b64 s[0:1], -1
	s_cbranch_vccnz .LBB0_973
	s_andn2_b64 vcc, exec, s[6:7]
	s_cbranch_vccnz .LBB0_972
	s_barrier
	s_branch .LBB0_972
